# component-0 softmax priority 1 also in the general (non-steady) bf16 attention loop
# speedup vs baseline: 1.0012x; 1.0012x over previous
; #define ATT_EVEN(j_, k2_, v1_) do { if (!F32) { if ((j_) + 2 < nt) ATT_DMAK((j_) + 2, k2_); if ((j_) + 1 < nt) ATT_DMAV((j_) + 1, v1_); } } while (0)
; template <bool F32>
; __device__ __forceinline__ void attn_unit(const AUnit& U, LAS unsigned char* lds, float lam, const float* subg) {
;     ...
;     if (comp == 0) {
; #pragma unroll 1
;         for (int it = 0; it <= nt; ++it) {
;             ATT_EVEN(it, r0, r2);
;             ATT_MM((it >= 1 && it <= mnt), (it < mnt), r0, r1);
;             if (it < mnt) ATT_SM(it);
.LBB0_747:
	v_add_u32_e32 v0, s92, v191
	v_add_u32_e32 v14, s92, v192
	v_add_u32_e32 v15, s92, v193
	v_add_u32_e32 v171, s92, v194
	v_add_u32_e32 v180, s92, v195
	v_add_u32_e32 v181, s92, v196
	v_add_u32_e32 v253, s92, v197
	v_add_u32_e32 v254, s92, v187
	v_add_u32_e32 v249, s29, v145
	v_add_u32_e32 v250, s29, v159
	v_add_u32_e32 v251, s29, v160
	v_add_u32_e32 v252, s29, v161
	ds_read_b64_tr_b16 v[2:3], v0 offset:49152
	ds_read_b64_tr_b16 v[4:5], v14 offset:49152
	ds_read_b64_tr_b16 v[6:7], v15 offset:49152
	ds_read_b64_tr_b16 v[8:9], v171 offset:49152
	ds_read_b64_tr_b16 v[10:11], v180 offset:49152
	ds_read_b64_tr_b16 v[12:13], v181 offset:49152
	ds_read_b64_tr_b16 v[172:173], v253 offset:49152
	ds_read_b64_tr_b16 v[174:175], v254 offset:49152
	ds_read_b64_tr_b16 v[198:199], v0 offset:53248
	ds_read_b64_tr_b16 v[200:201], v14 offset:53248
	ds_read_b64_tr_b16 v[202:203], v15 offset:53248
	ds_read_b64_tr_b16 v[204:205], v171 offset:53248
	ds_read_b64_tr_b16 v[206:207], v180 offset:53248
	ds_read_b64_tr_b16 v[208:209], v181 offset:53248
	s_setprio 2
	s_waitcnt lgkmcnt(12)
	v_mfma_f32_32x32x16_bf16 v[64:79], v[2:5], v[128:131], v[64:79]
	ds_read_b64_tr_b16 v[176:177], v253 offset:53248
	ds_read_b64_tr_b16 v[178:179], v254 offset:53248
	s_waitcnt lgkmcnt(12)
	v_mfma_f32_32x32x16_bf16 v[48:63], v[6:9], v[128:131], v[48:63]
	ds_read_b64_tr_b16 v[2:3], v0 offset:57344
	ds_read_b64_tr_b16 v[4:5], v14 offset:57344
	s_waitcnt lgkmcnt(12)
	v_mfma_f32_32x32x16_bf16 v[32:47], v[10:13], v[128:131], v[32:47]
	ds_read_b64_tr_b16 v[6:7], v15 offset:57344
	ds_read_b64_tr_b16 v[8:9], v171 offset:57344
	s_waitcnt lgkmcnt(12)
	v_mfma_f32_32x32x16_bf16 v[16:31], v[172:175], v[128:131], v[16:31]
	ds_read_b64_tr_b16 v[10:11], v180 offset:57344
	ds_read_b64_tr_b16 v[12:13], v181 offset:57344
	s_waitcnt lgkmcnt(12)
	v_mfma_f32_32x32x16_bf16 v[64:79], v[198:201], v[132:135], v[64:79]
	ds_read_b64_tr_b16 v[172:173], v253 offset:57344
	ds_read_b64_tr_b16 v[174:175], v254 offset:57344
	s_waitcnt lgkmcnt(12)
	v_mfma_f32_32x32x16_bf16 v[48:63], v[202:205], v[132:135], v[48:63]
	ds_read_b64_tr_b16 v[198:199], v0 offset:61440
	ds_read_b64_tr_b16 v[200:201], v14 offset:61440
	s_waitcnt lgkmcnt(12)
	v_mfma_f32_32x32x16_bf16 v[32:47], v[206:209], v[132:135], v[32:47]
	ds_read_b64_tr_b16 v[202:203], v15 offset:61440
	ds_read_b64_tr_b16 v[204:205], v171 offset:61440
	s_waitcnt lgkmcnt(12)
	v_mfma_f32_32x32x16_bf16 v[16:31], v[176:179], v[132:135], v[16:31]
	ds_read_b64_tr_b16 v[206:207], v180 offset:61440
	ds_read_b64_tr_b16 v[208:209], v181 offset:61440
	s_waitcnt lgkmcnt(12)
	v_mfma_f32_32x32x16_bf16 v[64:79], v[2:5], v[136:139], v[64:79]
	ds_read_b64_tr_b16 v[176:177], v253 offset:61440
	ds_read_b64_tr_b16 v[178:179], v254 offset:61440
	s_waitcnt lgkmcnt(12)
	v_mfma_f32_32x32x16_bf16 v[48:63], v[6:9], v[136:139], v[48:63]
	ds_read_b128 v[2:5], v249
	s_waitcnt lgkmcnt(11)
	v_mfma_f32_32x32x16_bf16 v[32:47], v[10:13], v[136:139], v[32:47]
	ds_read_b128 v[6:9], v249 offset:8192
	s_waitcnt lgkmcnt(10)
	v_mfma_f32_32x32x16_bf16 v[16:31], v[172:175], v[136:139], v[16:31]
	ds_read_b128 v[10:13], v250
	s_waitcnt lgkmcnt(9)
	v_mfma_f32_32x32x16_bf16 v[64:79], v[198:201], v[140:143], v[64:79]
	ds_read_b128 v[172:175], v250 offset:8192
	s_waitcnt lgkmcnt(8)
	v_mfma_f32_32x32x16_bf16 v[48:63], v[202:205], v[140:143], v[48:63]
	ds_read_b128 v[198:201], v251
	s_waitcnt lgkmcnt(7)
	v_mfma_f32_32x32x16_bf16 v[32:47], v[206:209], v[140:143], v[32:47]
	ds_read_b128 v[202:205], v251 offset:8192
	s_waitcnt lgkmcnt(6)
	v_mfma_f32_32x32x16_bf16 v[16:31], v[176:179], v[140:143], v[16:31]
	ds_read_b128 v[206:209], v252
	ds_read_b128 v[176:179], v252 offset:8192
	s_cmp_lt_i32 s31, s87
	s_cselect_b64 s[26:27], -1, 0
	s_cmp_ge_i32 s31, s87
	s_cbranch_scc1 .Lc0_noqk
	s_waitcnt lgkmcnt(7)
	v_mfma_f32_32x32x16_bf16 v[80:95], v[2:5], v[112:115], 0
	s_waitcnt lgkmcnt(6)
	v_mfma_f32_32x32x16_bf16 v[96:111], v[6:9], v[112:115], 0
	s_waitcnt lgkmcnt(5)
	v_mfma_f32_32x32x16_bf16 v[80:95], v[10:13], v[116:119], v[80:95]
	s_waitcnt lgkmcnt(4)
	v_mfma_f32_32x32x16_bf16 v[96:111], v[172:175], v[116:119], v[96:111]
	s_waitcnt lgkmcnt(3)
	v_mfma_f32_32x32x16_bf16 v[80:95], v[198:201], v[120:123], v[80:95]
	s_waitcnt lgkmcnt(2)
	v_mfma_f32_32x32x16_bf16 v[96:111], v[202:205], v[120:123], v[96:111]
	s_waitcnt lgkmcnt(1)
	v_mfma_f32_32x32x16_bf16 v[80:95], v[206:209], v[124:127], v[80:95]
	s_waitcnt lgkmcnt(0)
	v_mfma_f32_32x32x16_bf16 v[96:111], v[176:179], v[124:127], v[96:111]
	s_setprio 1
	s_branch .LBB0_749

.LBB0_748:
	s_add_i32 s94, s29, 0
	v_add_u32_e32 v0, s94, v145
	ds_read_b128 v[2:5], v0
	ds_read_b128 v[6:9], v0 offset:8192
	v_add_u32_e32 v0, s94, v159
	ds_read_b128 v[10:13], v0
	ds_read_b128 v[172:175], v0 offset:8192
	v_add_u32_e32 v0, s94, v160
	ds_read_b128 v[176:179], v0
	ds_read_b128 v[198:201], v0 offset:8192
	v_add_u32_e32 v0, s94, v161
	ds_read_b128 v[202:205], v0
	ds_read_b128 v[206:209], v0 offset:8192
	s_setprio 2
	s_waitcnt lgkmcnt(7)
	v_mfma_f32_32x32x16_bf16 v[80:95], v[2:5], v[112:115], 0
	s_waitcnt lgkmcnt(6)
	v_mfma_f32_32x32x16_bf16 v[96:111], v[6:9], v[112:115], 0
	s_waitcnt lgkmcnt(5)
	v_mfma_f32_32x32x16_bf16 v[80:95], v[10:13], v[116:119], v[80:95]
	s_waitcnt lgkmcnt(4)
	v_mfma_f32_32x32x16_bf16 v[96:111], v[172:175], v[116:119], v[96:111]
	s_waitcnt lgkmcnt(3)
	v_mfma_f32_32x32x16_bf16 v[80:95], v[176:179], v[120:123], v[80:95]
	s_waitcnt lgkmcnt(2)
	v_mfma_f32_32x32x16_bf16 v[96:111], v[198:201], v[120:123], v[96:111]
	s_waitcnt lgkmcnt(1)
	v_mfma_f32_32x32x16_bf16 v[80:95], v[202:205], v[124:127], v[80:95]
	s_waitcnt lgkmcnt(0)
	v_mfma_f32_32x32x16_bf16 v[96:111], v[206:209], v[124:127], v[96:111]
	s_setprio 1
	s_andn2_b64 vcc, exec, s[26:27]
	s_cbranch_vccnz .LBB0_742
